# panel-local seams: out-proj->up and up->down barriers are 4-workgroup per-panel barriers in the XCC-local placement
# speedup vs baseline: 1.0139x; 1.0139x over previous
; #define LAS __attribute__((address_space(3)))
; __global__ void __launch_bounds__(NWAVES * 64, 2) mk_fwd(Args args) {
;     extern __shared__ __attribute__((aligned(16))) unsigned char lds[];
;     Frame F; F.lds = (LAS unsigned char*)lds; F.wave = __builtin_amdgcn_readfirstlane((int)threadIdx.x >> 6); F.lane = 0; F.tid = 0; relaunder(F);
;     F.G = gridDim.x; { const int bx = blockIdx.x; F.vcu = (F.G % 8 == 0) ? (bx % 8) * (F.G / 8) + bx / 8 : bx; } F.cid = (int)blockIdx.x;
_Z6mk_fwd4Args:
	s_mov_b32 s101, 0
	s_load_dwordx2 s[92:93], s[0:1], 0x90
	s_load_dword s3, s[0:1], 0x98
	s_mov_b64 s[94:95], s[0:1]
	s_mov_b32 s0, -1
	s_add_u32 s4, s94, 0x98
	s_addc_u32 s5, s95, 0
	v_and_b32_e32 v161, 0x3ff, v0
	v_writelane_b32 v253, s4, 0
	s_waitcnt lgkmcnt(0)
	s_and_b32 s1, s3, 7
	v_readfirstlane_b32 s33, v161
	v_writelane_b32 v253, s5, 1
	s_cmp_lg_u32 s1, 0
	s_mov_b32 s96, s2
	s_cbranch_scc1 .LBB0_2
	s_ashr_i32 s4, s2, 31
	s_lshr_b32 s4, s4, 29
	s_add_i32 s4, s2, s4
	s_ashr_i32 s5, s4, 3
	s_and_b32 s4, s4, -8
	s_ashr_i32 s1, s3, 3
	s_sub_i32 s4, s2, s4
	s_mul_i32 s1, s1, s4
	s_add_i32 s96, s1, s5

; __device__ __forceinline__ unsigned xb_ld(unsigned* p)              { return __hip_atomic_load(p, __ATOMIC_RELAXED, __HIP_MEMORY_SCOPE_AGENT); }
; __device__ __forceinline__ void xcd_barrier_complete(unsigned* bar, unsigned x, unsigned& nloc, unsigned& nx, unsigned& uni) {
;     const unsigned G = gridDim.x * gridDim.y * gridDim.z;
;     unsigned sum, cnt, mine, sp = 0u;
;     for (;;) {
;         sum = 0u; cnt = 0u; mine = 0u;
; #pragma unroll
;         for (unsigned j = 0; j < 16; ++j) { const unsigned c = xb_ld(&bar[XB_XCNT(j)]); sum += c; cnt += (c > 0u) ? 1u : 0u; mine = (j == x) ? c : mine; }
; __device__ __forceinline__ void xcd_barrier(const XcdBarrier& b, const bool local_only = false) {
;     asm volatile("s_waitcnt vmcnt(0)" ::: "memory");
;     __syncthreads();
;     if (threadIdx.x == 0) {
;         unsigned* bar = b.bar;
;         __builtin_amdgcn_s_waitcnt(0);
;         unsigned nloc = b.st[0], nx = b.st[1];
;         if (nloc == 0u) { unsigned uni; xcd_barrier_complete(bar, b.x, nloc, nx, uni); b.st[0] = nloc; b.st[1] = nx; b.st[2] = uni; }
.LBB0_271:
	s_mov_b32 s101, 0
	v_readlane_b32 s0, v253, 6
	s_add_i32 s48, s0, 1
	s_cmp_ge_i32 s48, s93
	s_cbranch_scc1 .LBB0_326
	s_waitcnt vmcnt(0)
	s_waitcnt vmcnt(0) lgkmcnt(0)
	s_barrier
	s_mov_b64 s[0:1], exec
	v_readlane_b32 s4, v254, 18
	v_readlane_b32 s5, v254, 19
	s_and_b64 s[4:5], s[0:1], s[4:5]
	s_mov_b64 exec, s[4:5]
	s_cbranch_execz .LBB0_325
	v_readlane_b32 s4, v254, 62
	s_waitcnt vmcnt(0) expcnt(0) lgkmcnt(0)
	s_nop 0
	v_mov_b32_e32 v0, s4
	ds_read_b32 v0, v0
	v_readlane_b32 s4, v254, 63
	s_waitcnt lgkmcnt(0)
	v_cmp_ne_u32_e32 vcc, 0, v0
	v_mov_b32_e32 v1, s4
	ds_read_b32 v6, v1
	s_cbranch_vccnz .LBB0_287
	s_add_u32 s60, s24, 0x1200
	s_addc_u32 s61, s25, 0
	s_add_u32 s52, s24, 0x1400
	s_addc_u32 s53, s25, 0
	s_add_u32 s56, s24, 0x1500
	s_addc_u32 s57, s25, 0
	s_add_u32 s54, s24, 0x1600
	s_addc_u32 s55, s25, 0
	s_add_u32 s50, s24, 0x1700
	s_addc_u32 s51, s25, 0
	s_add_u32 s46, s24, 0x1800
	s_addc_u32 s47, s25, 0
	s_add_u32 s44, s24, 0x1900
	s_addc_u32 s45, s25, 0
	s_add_u32 s42, s24, 0x1a00
	s_addc_u32 s43, s25, 0
	s_add_u32 s40, s24, 0x1b00
	s_addc_u32 s41, s25, 0
	s_add_u32 s38, s24, 0x1c00
	s_addc_u32 s39, s25, 0
	s_add_u32 s28, s24, 0x1d00
	v_readlane_b32 s6, v253, 0
	s_addc_u32 s29, s25, 0
	v_readlane_b32 s7, v253, 1
	s_add_u32 s26, s24, 0x1e00
	s_load_dwordx2 s[4:5], s[6:7], 0x4
	s_addc_u32 s27, s25, 0
	s_add_u32 s22, s24, 0x1f00
	s_addc_u32 s23, s25, 0
	s_add_u32 s20, s24, 0x2000
	s_addc_u32 s21, s25, 0
	s_waitcnt lgkmcnt(0)
	s_mul_i32 s66, s4, s3
	s_add_u32 s4, s24, 0x2100
	s_mul_i32 s66, s66, s5
	s_addc_u32 s5, s25, 0
	s_add_u32 s6, s24, 0x2200
	s_addc_u32 s7, s25, 0
	s_add_u32 s18, s24, 0x2300
	s_addc_u32 s19, s25, 0
	s_mov_b32 s67, 1
	s_branch .LBB0_276

; __device__ __forceinline__ unsigned xb_ld(unsigned* p)              { return __hip_atomic_load(p, __ATOMIC_RELAXED, __HIP_MEMORY_SCOPE_AGENT); }
; __device__ __forceinline__ unsigned xb_add(unsigned* p, unsigned v) { return __hip_atomic_fetch_add(p, v, __ATOMIC_RELAXED, __HIP_MEMORY_SCOPE_AGENT); }
; #define XB_SPIN(cond, bar) do { unsigned _sp = 0; while (cond) { __builtin_amdgcn_s_sleep(1); \
;     if ((++_sp & 255u) == 0u) { if (xb_ld(&(bar)[XB_TMO])) break; if (_sp > XB_SPIN_CAP) { atomicAdd(&(bar)[XB_TMO], 1u); break; } } } } while (0)
; __device__ __forceinline__ void xcd_barrier(const XcdBarrier& b, const bool local_only = false) {
;     ...
;         const unsigned old = xb_add(&bar[XB_XSUB(b.x)], 1u);
;         const unsigned gen = old / nloc;
;         if (old + 1u == (gen + 1u) * nloc) {
;             if (!local_only) {
;             __builtin_amdgcn_fence(__ATOMIC_RELEASE, "agent");
;             asm volatile("s_waitcnt vmcnt(0)" ::: "memory");
;             const unsigned og = xb_add(&bar[XB_TOP], 1u);
;             const unsigned tg = og / nx;
;             if (og + 1u == (tg + 1u) * nx) xb_add(&bar[XB_TOPGEN], 1u);
;             else XB_SPIN(xb_ld(&bar[XB_TOPGEN]) == tg, bar);
;             }
;             __builtin_amdgcn_fence(__ATOMIC_ACQUIRE, "agent");
;             xb_add(&bar[XB_XGEN(b.x)], 1u);
;             asm volatile("s_waitcnt vmcnt(0)" ::: "memory");
;         } else {
;             XB_SPIN(xb_ld(&bar[XB_XGEN(b.x)]) == gen, bar);
.LBB0_287:
	v_readlane_b32 s4, v254, 13
	s_lshl_b32 s4, s4, 2
	s_mov_b64 s[6:7], exec
	s_add_u32 s4, s24, s4
	s_addc_u32 s5, s25, 0
	v_mbcnt_lo_u32_b32 v1, s6, 0
	s_add_u32 s4, s4, 0x1000
	v_mbcnt_hi_u32_b32 v1, s7, v1
	s_addc_u32 s5, s5, 0
	s_mov_b32 s100, 0x1000
	s_cmp_eq_u32 s101, 0
	s_cbranch_scc1 .Lmy_pb_0
	v_readlane_b32 vcc_lo, v253, 2
	v_readlane_b32 vcc_hi, v253, 3
	s_nop 0
	s_and_b64 vcc, exec, vcc
	s_cbranch_vccnz .Lmy_pb_0
	s_lshr_b32 s100, s96, 5
	s_mul_i32 s100, s100, 7
	s_and_b32 vcc_lo, s96, 7
	s_add_u32 s100, s100, vcc_lo
	s_lshl_b32 s100, s100, 8
	s_add_u32 s100, s100, 0x7c00
	v_mov_b32_e32 v0, 4
.Lmy_pb_0:
	v_cmp_eq_u32_e32 vcc, 0, v1
	s_and_saveexec_b64 s[14:15], vcc
	s_cbranch_execz .LBB0_289
	s_bcnt1_i32_b64 s6, s[6:7]
	v_mov_b32_e32 v2, s6
	v_mov_b32_e32 v3, s100
	global_atomic_add v2, v3, v2, s[4:5] offset:1024 sc0
.LBB0_289:
	s_or_b64 exec, exec, s[14:15]
	buffer_inv sc1
	v_cvt_f32_u32_e32 v3, v0
	s_waitcnt vmcnt(0)
	v_readfirstlane_b32 s6, v2
	v_sub_u32_e32 v2, 0, v0
	v_rcp_iflag_f32_e32 v3, v3
	v_add_u32_e32 v4, s6, v1
	v_mul_f32_e32 v3, 0x4f7ffffe, v3
	v_cvt_u32_f32_e32 v3, v3
	v_mul_lo_u32 v1, v2, v3
	v_mul_hi_u32 v1, v3, v1
	v_add_u32_e32 v1, v3, v1
	v_mul_hi_u32 v1, v4, v1
	v_mul_lo_u32 v2, v1, v0
	v_sub_u32_e32 v2, v4, v2
	v_add_u32_e32 v3, 1, v1
	v_cmp_ge_u32_e32 vcc, v2, v0
	s_nop 1
	v_cndmask_b32_e32 v1, v1, v3, vcc
	v_sub_u32_e32 v3, v2, v0
	v_cndmask_b32_e32 v2, v2, v3, vcc
	v_add_u32_e32 v3, 1, v1
	v_cmp_ge_u32_e32 vcc, v2, v0
	v_add_u32_e32 v2, 1, v4
	s_nop 0
	v_cndmask_b32_e32 v1, v1, v3, vcc
	v_mul_lo_u32 v3, v0, v1
	v_add_u32_e32 v0, v3, v0
	v_cmp_ne_u32_e32 vcc, v2, v0
	s_and_saveexec_b64 s[6:7], vcc
	s_xor_b64 s[6:7], exec, s[6:7]
	s_cbranch_execz .LBB0_303
	v_readlane_b32 vcc_lo, v253, 2
	v_readlane_b32 vcc_hi, v253, 3
	s_nop 0
	s_and_b64 vcc, exec, vcc
	s_cbranch_vccnz .Lxb_gen_1
	v_mov_b32_e32 v4, v0
	v_mov_b32_e32 v5, s100
	s_mov_b32 s20, 0

; __device__ __forceinline__ unsigned xb_ld(unsigned* p)              { return __hip_atomic_load(p, __ATOMIC_RELAXED, __HIP_MEMORY_SCOPE_AGENT); }
; __device__ __forceinline__ void xcd_barrier_complete(unsigned* bar, unsigned x, unsigned& nloc, unsigned& nx, unsigned& uni) {
;     const unsigned G = gridDim.x * gridDim.y * gridDim.z;
;     unsigned sum, cnt, mine, sp = 0u;
;     for (;;) {
;         sum = 0u; cnt = 0u; mine = 0u;
; #pragma unroll
;         for (unsigned j = 0; j < 16; ++j) { const unsigned c = xb_ld(&bar[XB_XCNT(j)]); sum += c; cnt += (c > 0u) ? 1u : 0u; mine = (j == x) ? c : mine; }
; __device__ __forceinline__ void xcd_barrier(const XcdBarrier& b, const bool local_only = false) {
;     asm volatile("s_waitcnt vmcnt(0)" ::: "memory");
;     __syncthreads();
;     if (threadIdx.x == 0) {
;         unsigned* bar = b.bar;
;         __builtin_amdgcn_s_waitcnt(0);
;         unsigned nloc = b.st[0], nx = b.st[1];
;         if (nloc == 0u) { unsigned uni; xcd_barrier_complete(bar, b.x, nloc, nx, uni); b.st[0] = nloc; b.st[1] = nx; b.st[2] = uni; }
.LBB0_437:
	s_mov_b32 s101, 0
	v_readlane_b32 s0, v253, 6
	s_add_i32 s48, s0, 2
	s_cmp_ge_i32 s48, s93
	s_cbranch_scc1 .LBB0_448
	s_waitcnt vmcnt(0)
	s_barrier
	s_mov_b64 s[0:1], exec
	v_readlane_b32 s4, v254, 18
	v_readlane_b32 s5, v254, 19
	s_and_b64 s[4:5], s[0:1], s[4:5]
	v_mov_b32_e32 v237, v202
	s_mov_b64 exec, s[4:5]
	s_cbranch_execz .LBB0_492
	v_readlane_b32 s4, v254, 62
	s_waitcnt vmcnt(0) expcnt(0) lgkmcnt(0)
	s_nop 0
	v_mov_b32_e32 v0, s4
	ds_read_b32 v0, v0
	v_readlane_b32 s4, v254, 63
	s_waitcnt lgkmcnt(0)
	v_cmp_ne_u32_e32 vcc, 0, v0
	v_mov_b32_e32 v1, s4
	ds_read_b32 v6, v1
	s_cbranch_vccnz .LBB0_454
	s_add_u32 s58, s24, 0x1200
	s_addc_u32 s59, s25, 0
	s_add_u32 s50, s24, 0x1400
	s_addc_u32 s51, s25, 0
	s_add_u32 s54, s24, 0x1500
	s_addc_u32 s55, s25, 0
	s_add_u32 s52, s24, 0x1600
	s_addc_u32 s53, s25, 0
	s_add_u32 s46, s24, 0x1700
	s_addc_u32 s47, s25, 0
	s_add_u32 s44, s24, 0x1800
	s_addc_u32 s45, s25, 0
	s_add_u32 s42, s24, 0x1900
	s_addc_u32 s43, s25, 0
	s_add_u32 s40, s24, 0x1a00
	s_addc_u32 s41, s25, 0
	s_add_u32 s38, s24, 0x1b00
	s_addc_u32 s39, s25, 0
	s_add_u32 s28, s24, 0x1c00
	s_addc_u32 s29, s25, 0
	s_add_u32 s26, s24, 0x1d00
	v_readlane_b32 s6, v253, 0
	s_addc_u32 s27, s25, 0
	v_readlane_b32 s7, v253, 1
	s_add_u32 s22, s24, 0x1e00
	s_load_dwordx2 s[4:5], s[6:7], 0x4
	s_addc_u32 s23, s25, 0
	s_add_u32 s20, s24, 0x1f00
	s_addc_u32 s21, s25, 0
	s_add_u32 s18, s24, 0x2000
	s_addc_u32 s19, s25, 0
	s_waitcnt lgkmcnt(0)
	s_mul_i32 s66, s4, s3
	s_add_u32 s4, s24, 0x2100
	s_mul_i32 s66, s66, s5
	s_addc_u32 s5, s25, 0
	s_add_u32 s6, s24, 0x2200
	s_addc_u32 s7, s25, 0
	s_add_u32 s8, s24, 0x2300
	s_addc_u32 s9, s25, 0
	s_mov_b32 s67, 1
	s_branch .LBB0_442

; __device__ __forceinline__ unsigned xb_ld(unsigned* p)              { return __hip_atomic_load(p, __ATOMIC_RELAXED, __HIP_MEMORY_SCOPE_AGENT); }
; __device__ __forceinline__ unsigned xb_add(unsigned* p, unsigned v) { return __hip_atomic_fetch_add(p, v, __ATOMIC_RELAXED, __HIP_MEMORY_SCOPE_AGENT); }
; #define XB_SPIN(cond, bar) do { unsigned _sp = 0; while (cond) { __builtin_amdgcn_s_sleep(1); \
;     if ((++_sp & 255u) == 0u) { if (xb_ld(&(bar)[XB_TMO])) break; if (_sp > XB_SPIN_CAP) { atomicAdd(&(bar)[XB_TMO], 1u); break; } } } } while (0)
; __device__ __forceinline__ void xcd_barrier(const XcdBarrier& b, const bool local_only = false) {
;     ...
;         const unsigned old = xb_add(&bar[XB_XSUB(b.x)], 1u);
;         const unsigned gen = old / nloc;
;         if (old + 1u == (gen + 1u) * nloc) {
;             if (!local_only) {
;             __builtin_amdgcn_fence(__ATOMIC_RELEASE, "agent");
;             asm volatile("s_waitcnt vmcnt(0)" ::: "memory");
;             const unsigned og = xb_add(&bar[XB_TOP], 1u);
;             const unsigned tg = og / nx;
;             if (og + 1u == (tg + 1u) * nx) xb_add(&bar[XB_TOPGEN], 1u);
;             else XB_SPIN(xb_ld(&bar[XB_TOPGEN]) == tg, bar);
;             }
;             __builtin_amdgcn_fence(__ATOMIC_ACQUIRE, "agent");
;             xb_add(&bar[XB_XGEN(b.x)], 1u);
;             asm volatile("s_waitcnt vmcnt(0)" ::: "memory");
;         } else {
;             XB_SPIN(xb_ld(&bar[XB_XGEN(b.x)]) == gen, bar);
.Lmy_pb_1:
	v_cmp_eq_u32_e32 vcc, 0, v1
	s_and_saveexec_b64 s[8:9], vcc
	s_cbranch_execz .LBB0_456
	s_bcnt1_i32_b64 s6, s[6:7]
	v_mov_b32_e32 v2, s6
	v_mov_b32_e32 v3, s100
	global_atomic_add v2, v3, v2, s[4:5] offset:1024 sc0
.LBB0_456:
	s_or_b64 exec, exec, s[8:9]
	buffer_inv sc1
	v_cvt_f32_u32_e32 v3, v0
	s_waitcnt vmcnt(0)
	v_readfirstlane_b32 s6, v2
	v_sub_u32_e32 v2, 0, v0
	v_rcp_iflag_f32_e32 v3, v3
	v_add_u32_e32 v4, s6, v1
	v_mul_f32_e32 v3, 0x4f7ffffe, v3
	v_cvt_u32_f32_e32 v3, v3
	v_mul_lo_u32 v1, v2, v3
	v_mul_hi_u32 v1, v3, v1
	v_add_u32_e32 v1, v3, v1
	v_mul_hi_u32 v1, v4, v1
	v_mul_lo_u32 v2, v1, v0
	v_sub_u32_e32 v2, v4, v2
	v_add_u32_e32 v3, 1, v1
	v_cmp_ge_u32_e32 vcc, v2, v0
	s_nop 1
	v_cndmask_b32_e32 v1, v1, v3, vcc
	v_sub_u32_e32 v3, v2, v0
	v_cndmask_b32_e32 v2, v2, v3, vcc
	v_add_u32_e32 v3, 1, v1
	v_cmp_ge_u32_e32 vcc, v2, v0
	v_add_u32_e32 v2, 1, v4
	s_nop 0
	v_cndmask_b32_e32 v1, v1, v3, vcc
	v_mul_lo_u32 v3, v0, v1
	v_add_u32_e32 v0, v3, v0
	v_cmp_ne_u32_e32 vcc, v2, v0
	s_and_saveexec_b64 s[6:7], vcc
	s_xor_b64 s[6:7], exec, s[6:7]
	s_cbranch_execz .LBB0_470
	v_readlane_b32 vcc_lo, v253, 2
	v_readlane_b32 vcc_hi, v253, 3
	s_nop 0
	s_and_b64 vcc, exec, vcc
	s_cbranch_vccnz .Lxb_gen_2
	v_mov_b32_e32 v4, v0
	v_mov_b32_e32 v5, s100
	s_mov_b32 s18, 0

; __device__ __forceinline__ unsigned xb_ld(unsigned* p)              { return __hip_atomic_load(p, __ATOMIC_RELAXED, __HIP_MEMORY_SCOPE_AGENT); }
; __device__ __forceinline__ void xcd_barrier_complete(unsigned* bar, unsigned x, unsigned& nloc, unsigned& nx, unsigned& uni) {
;     const unsigned G = gridDim.x * gridDim.y * gridDim.z;
;     unsigned sum, cnt, mine, sp = 0u;
;     for (;;) {
;         sum = 0u; cnt = 0u; mine = 0u;
; #pragma unroll
;         for (unsigned j = 0; j < 16; ++j) { const unsigned c = xb_ld(&bar[XB_XCNT(j)]); sum += c; cnt += (c > 0u) ? 1u : 0u; mine = (j == x) ? c : mine; }
; __device__ __forceinline__ void xcd_barrier(const XcdBarrier& b, const bool local_only = false) {
;     asm volatile("s_waitcnt vmcnt(0)" ::: "memory");
;     __syncthreads();
;     if (threadIdx.x == 0) {
;         unsigned* bar = b.bar;
;         __builtin_amdgcn_s_waitcnt(0);
;         unsigned nloc = b.st[0], nx = b.st[1];
;         if (nloc == 0u) { unsigned uni; xcd_barrier_complete(bar, b.x, nloc, nx, uni); b.st[0] = nloc; b.st[1] = nx; b.st[2] = uni; }
.LBB0_534:
	s_mov_b32 s101, 1
	v_readlane_b32 s4, v253, 6
	s_add_i32 s4, s4, 3
	s_cmp_ge_i32 s4, s93
	s_mov_b64 s[4:5], 0
	s_cbranch_scc1 .LBB0_590
	s_waitcnt vmcnt(0)
	s_waitcnt vmcnt(0) lgkmcnt(0)
	s_barrier
	s_mov_b64 s[8:9], exec
	v_readlane_b32 s4, v254, 18
	v_readlane_b32 s5, v254, 19
	s_and_b64 s[4:5], s[8:9], s[4:5]
	s_mov_b64 exec, s[4:5]
	s_cbranch_execz .LBB0_589
	v_readlane_b32 s4, v254, 62
	s_waitcnt vmcnt(0) expcnt(0) lgkmcnt(0)
	s_nop 0
	v_mov_b32_e32 v0, s4
	ds_read_b32 v0, v0
	v_readlane_b32 s4, v254, 63
	s_waitcnt lgkmcnt(0)
	v_cmp_ne_u32_e32 vcc, 0, v0
	v_mov_b32_e32 v1, s4
	ds_read_b32 v6, v1
	s_cbranch_vccnz .LBB0_551
	s_add_u32 s60, s18, 0x1200
	s_addc_u32 s61, s19, 0
	s_add_u32 s52, s18, 0x1400
	s_addc_u32 s53, s19, 0
	s_add_u32 s56, s18, 0x1500
	s_addc_u32 s57, s19, 0
	s_add_u32 s54, s18, 0x1600
	s_addc_u32 s55, s19, 0
	s_add_u32 s50, s18, 0x1700
	s_addc_u32 s51, s19, 0
	s_add_u32 s46, s18, 0x1800
	s_addc_u32 s47, s19, 0
	s_add_u32 s44, s18, 0x1900
	s_addc_u32 s45, s19, 0
	s_add_u32 s42, s18, 0x1a00
	s_addc_u32 s43, s19, 0
	s_add_u32 s40, s18, 0x1b00
	s_addc_u32 s41, s19, 0
	s_add_u32 s38, s18, 0x1c00
	s_addc_u32 s39, s19, 0
	s_add_u32 s28, s18, 0x1d00
	v_readlane_b32 s6, v253, 0
	s_addc_u32 s29, s19, 0
	v_readlane_b32 s7, v253, 1
	s_add_u32 s26, s18, 0x1e00
	s_load_dwordx2 s[4:5], s[6:7], 0x4
	s_addc_u32 s27, s19, 0
	s_add_u32 s24, s18, 0x1f00
	s_addc_u32 s25, s19, 0
	s_add_u32 s22, s18, 0x2000
	s_addc_u32 s23, s19, 0
	s_waitcnt lgkmcnt(0)
	s_mul_i32 s48, s4, s3
	s_add_u32 s4, s18, 0x2100
	s_mul_i32 s48, s48, s5
	s_addc_u32 s5, s19, 0
	s_add_u32 s6, s18, 0x2200
	s_addc_u32 s7, s19, 0
	s_add_u32 s20, s18, 0x2300
	s_addc_u32 s21, s19, 0
	s_mov_b32 s66, 1
	s_branch .LBB0_539

; __device__ __forceinline__ unsigned xb_add(unsigned* p, unsigned v) { return __hip_atomic_fetch_add(p, v, __ATOMIC_RELAXED, __HIP_MEMORY_SCOPE_AGENT); }
; __device__ __forceinline__ void xcd_barrier(const XcdBarrier& b, const bool local_only = false) {
;     ...
;         const unsigned old = xb_add(&bar[XB_XSUB(b.x)], 1u);
;         const unsigned gen = old / nloc;
;         if (old + 1u == (gen + 1u) * nloc) {
.LBB0_551:
	v_readlane_b32 s4, v254, 13
	s_lshl_b32 s4, s4, 2
	s_mov_b64 s[6:7], exec
	s_add_u32 s4, s18, s4
	s_addc_u32 s5, s19, 0
	v_mbcnt_lo_u32_b32 v1, s6, 0
	s_add_u32 s4, s4, 0x1000
	v_mbcnt_hi_u32_b32 v1, s7, v1
	s_addc_u32 s5, s5, 0
	s_mov_b32 s100, 0x1000
	s_cmp_eq_u32 s101, 0
	s_cbranch_scc1 .Lmy_pb_2
	v_readlane_b32 vcc_lo, v253, 2
	v_readlane_b32 vcc_hi, v253, 3
	s_nop 0
	s_and_b64 vcc, exec, vcc
	s_cbranch_vccnz .Lmy_pb_2
	s_lshr_b32 s100, s96, 5
	s_mul_i32 s100, s100, 7
	s_and_b32 vcc_lo, s96, 7
	s_add_u32 s100, s100, vcc_lo
	s_lshl_b32 s100, s100, 8
	s_add_u32 s100, s100, 0x7c00
	v_mov_b32_e32 v0, 4

; __device__ __forceinline__ unsigned xb_ld(unsigned* p)              { return __hip_atomic_load(p, __ATOMIC_RELAXED, __HIP_MEMORY_SCOPE_AGENT); }
; __device__ __forceinline__ unsigned xb_add(unsigned* p, unsigned v) { return __hip_atomic_fetch_add(p, v, __ATOMIC_RELAXED, __HIP_MEMORY_SCOPE_AGENT); }
; #define XB_SPIN(cond, bar) do { unsigned _sp = 0; while (cond) { __builtin_amdgcn_s_sleep(1); \
;     if ((++_sp & 255u) == 0u) { if (xb_ld(&(bar)[XB_TMO])) break; if (_sp > XB_SPIN_CAP) { atomicAdd(&(bar)[XB_TMO], 1u); break; } } } } while (0)
; __device__ __forceinline__ void xcd_barrier(const XcdBarrier& b, const bool local_only = false) {
;     ...
;         const unsigned old = xb_add(&bar[XB_XSUB(b.x)], 1u);
;         const unsigned gen = old / nloc;
;         if (old + 1u == (gen + 1u) * nloc) {
;             if (!local_only) {
;             __builtin_amdgcn_fence(__ATOMIC_RELEASE, "agent");
;             asm volatile("s_waitcnt vmcnt(0)" ::: "memory");
;             const unsigned og = xb_add(&bar[XB_TOP], 1u);
;             const unsigned tg = og / nx;
;             if (og + 1u == (tg + 1u) * nx) xb_add(&bar[XB_TOPGEN], 1u);
;             else XB_SPIN(xb_ld(&bar[XB_TOPGEN]) == tg, bar);
;             }
;             __builtin_amdgcn_fence(__ATOMIC_ACQUIRE, "agent");
;             xb_add(&bar[XB_XGEN(b.x)], 1u);
;             asm volatile("s_waitcnt vmcnt(0)" ::: "memory");
;         } else {
;             XB_SPIN(xb_ld(&bar[XB_XGEN(b.x)]) == gen, bar);
.LBB0_553:
	s_or_b64 exec, exec, s[14:15]
	buffer_inv sc1
	v_cvt_f32_u32_e32 v3, v0
	s_waitcnt vmcnt(0)
	v_readfirstlane_b32 s6, v2
	v_sub_u32_e32 v2, 0, v0
	v_rcp_iflag_f32_e32 v3, v3
	v_add_u32_e32 v4, s6, v1
	v_mul_f32_e32 v3, 0x4f7ffffe, v3
	v_cvt_u32_f32_e32 v3, v3
	v_mul_lo_u32 v1, v2, v3
	v_mul_hi_u32 v1, v3, v1
	v_add_u32_e32 v1, v3, v1
	v_mul_hi_u32 v1, v4, v1
	v_mul_lo_u32 v2, v1, v0
	v_sub_u32_e32 v2, v4, v2
	v_add_u32_e32 v3, 1, v1
	v_cmp_ge_u32_e32 vcc, v2, v0
	s_nop 1
	v_cndmask_b32_e32 v1, v1, v3, vcc
	v_sub_u32_e32 v3, v2, v0
	v_cndmask_b32_e32 v2, v2, v3, vcc
	v_add_u32_e32 v3, 1, v1
	v_cmp_ge_u32_e32 vcc, v2, v0
	v_add_u32_e32 v2, 1, v4
	s_nop 0
	v_cndmask_b32_e32 v1, v1, v3, vcc
	v_mul_lo_u32 v3, v0, v1
	v_add_u32_e32 v0, v3, v0
	v_cmp_ne_u32_e32 vcc, v2, v0
	s_and_saveexec_b64 s[6:7], vcc
	s_xor_b64 s[6:7], exec, s[6:7]
	s_cbranch_execz .LBB0_567
	v_readlane_b32 vcc_lo, v253, 2
	v_readlane_b32 vcc_hi, v253, 3
	s_nop 0
	s_and_b64 vcc, exec, vcc
	s_cbranch_vccnz .Lxb_gen_3
	v_mov_b32_e32 v4, v0
	v_mov_b32_e32 v5, s100
	s_mov_b32 s22, 0

; __device__ __forceinline__ unsigned xb_ld(unsigned* p)              { return __hip_atomic_load(p, __ATOMIC_RELAXED, __HIP_MEMORY_SCOPE_AGENT); }
; __device__ __forceinline__ void xcd_barrier_complete(unsigned* bar, unsigned x, unsigned& nloc, unsigned& nx, unsigned& uni) {
;     const unsigned G = gridDim.x * gridDim.y * gridDim.z;
;     unsigned sum, cnt, mine, sp = 0u;
;     for (;;) {
;         sum = 0u; cnt = 0u; mine = 0u;
; #pragma unroll
;         for (unsigned j = 0; j < 16; ++j) { const unsigned c = xb_ld(&bar[XB_XCNT(j)]); sum += c; cnt += (c > 0u) ? 1u : 0u; mine = (j == x) ? c : mine; }
; __device__ __forceinline__ void xcd_barrier(const XcdBarrier& b, const bool local_only = false) {
;     asm volatile("s_waitcnt vmcnt(0)" ::: "memory");
;     __syncthreads();
;     if (threadIdx.x == 0) {
;         unsigned* bar = b.bar;
;         __builtin_amdgcn_s_waitcnt(0);
;         unsigned nloc = b.st[0], nx = b.st[1];
;         if (nloc == 0u) { unsigned uni; xcd_barrier_complete(bar, b.x, nloc, nx, uni); b.st[0] = nloc; b.st[1] = nx; b.st[2] = uni; }
.LBB0_656:
	s_mov_b32 s101, 0
	v_readlane_b32 s0, v253, 6
	s_add_i32 s48, s0, 1
	s_cmp_ge_i32 s48, s93
	s_cbranch_scc1 .LBB0_711
	s_waitcnt vmcnt(0)
	s_waitcnt vmcnt(0)
	s_barrier
	s_mov_b64 s[0:1], exec
	v_readlane_b32 s4, v254, 18
	v_readlane_b32 s5, v254, 19
	s_and_b64 s[4:5], s[0:1], s[4:5]
	s_mov_b64 exec, s[4:5]
	s_cbranch_execz .LBB0_710
	v_readlane_b32 s4, v254, 62
	s_waitcnt vmcnt(0) expcnt(0) lgkmcnt(0)
	s_nop 0
	v_mov_b32_e32 v0, s4
	ds_read_b32 v0, v0
	v_readlane_b32 s4, v254, 63
	s_waitcnt lgkmcnt(0)
	v_cmp_ne_u32_e32 vcc, 0, v0
	v_mov_b32_e32 v1, s4
	ds_read_b32 v6, v1
	s_cbranch_vccnz .LBB0_672
	s_add_u32 s56, s8, 0x1200
	s_addc_u32 s57, s9, 0
	s_add_u32 s46, s8, 0x1400
	s_addc_u32 s47, s9, 0
	s_add_u32 s52, s8, 0x1500
	s_addc_u32 s53, s9, 0
	s_add_u32 s50, s8, 0x1600
	s_addc_u32 s51, s9, 0
	s_add_u32 s44, s8, 0x1700
	s_addc_u32 s45, s9, 0
	s_add_u32 s42, s8, 0x1800
	s_addc_u32 s43, s9, 0
	s_add_u32 s40, s8, 0x1900
	s_addc_u32 s41, s9, 0
	s_add_u32 s38, s8, 0x1a00
	s_addc_u32 s39, s9, 0
	s_add_u32 s28, s8, 0x1b00
	s_addc_u32 s29, s9, 0
	s_add_u32 s26, s8, 0x1c00
	s_addc_u32 s27, s9, 0
	s_add_u32 s24, s8, 0x1d00
	v_readlane_b32 s6, v253, 0
	s_addc_u32 s25, s9, 0
	v_readlane_b32 s7, v253, 1
	s_add_u32 s22, s8, 0x1e00
	s_load_dwordx2 s[4:5], s[6:7], 0x4
	s_addc_u32 s23, s9, 0
	s_add_u32 s20, s8, 0x1f00
	s_addc_u32 s21, s9, 0
	s_add_u32 s18, s8, 0x2000
	s_addc_u32 s19, s9, 0
	s_waitcnt lgkmcnt(0)
	s_mul_i32 s62, s4, s3
	s_add_u32 s4, s8, 0x2100
	s_mul_i32 s62, s62, s5
	s_addc_u32 s5, s9, 0
	s_add_u32 s6, s8, 0x2200
	s_addc_u32 s7, s9, 0
	s_add_u32 s12, s8, 0x2300
	s_addc_u32 s13, s9, 0
	s_mov_b32 s63, 1
	s_branch .LBB0_661

; __device__ __forceinline__ unsigned xb_ld(unsigned* p)              { return __hip_atomic_load(p, __ATOMIC_RELAXED, __HIP_MEMORY_SCOPE_AGENT); }
; __device__ __forceinline__ unsigned xb_add(unsigned* p, unsigned v) { return __hip_atomic_fetch_add(p, v, __ATOMIC_RELAXED, __HIP_MEMORY_SCOPE_AGENT); }
; #define XB_SPIN(cond, bar) do { unsigned _sp = 0; while (cond) { __builtin_amdgcn_s_sleep(1); \
;     if ((++_sp & 255u) == 0u) { if (xb_ld(&(bar)[XB_TMO])) break; if (_sp > XB_SPIN_CAP) { atomicAdd(&(bar)[XB_TMO], 1u); break; } } } } while (0)
; __device__ __forceinline__ void xcd_barrier(const XcdBarrier& b, const bool local_only = false) {
;     ...
;         const unsigned old = xb_add(&bar[XB_XSUB(b.x)], 1u);
;         const unsigned gen = old / nloc;
;         if (old + 1u == (gen + 1u) * nloc) {
;             if (!local_only) {
;             __builtin_amdgcn_fence(__ATOMIC_RELEASE, "agent");
;             asm volatile("s_waitcnt vmcnt(0)" ::: "memory");
;             const unsigned og = xb_add(&bar[XB_TOP], 1u);
;             const unsigned tg = og / nx;
;             if (og + 1u == (tg + 1u) * nx) xb_add(&bar[XB_TOPGEN], 1u);
;             else XB_SPIN(xb_ld(&bar[XB_TOPGEN]) == tg, bar);
;             }
;             __builtin_amdgcn_fence(__ATOMIC_ACQUIRE, "agent");
;             xb_add(&bar[XB_XGEN(b.x)], 1u);
;             asm volatile("s_waitcnt vmcnt(0)" ::: "memory");
;         } else {
;             XB_SPIN(xb_ld(&bar[XB_XGEN(b.x)]) == gen, bar);
.LBB0_672:
	v_readlane_b32 s4, v254, 13
	s_lshl_b32 s4, s4, 2
	s_mov_b64 s[6:7], exec
	s_add_u32 s4, s8, s4
	s_addc_u32 s5, s9, 0
	v_mbcnt_lo_u32_b32 v1, s6, 0
	s_add_u32 s4, s4, 0x1000
	v_mbcnt_hi_u32_b32 v1, s7, v1
	s_addc_u32 s5, s5, 0
	s_mov_b32 s100, 0x1000
	s_cmp_eq_u32 s101, 0
	s_cbranch_scc1 .Lmy_pb_3
	v_readlane_b32 vcc_lo, v253, 2
	v_readlane_b32 vcc_hi, v253, 3
	s_nop 0
	s_and_b64 vcc, exec, vcc
	s_cbranch_vccnz .Lmy_pb_3
	s_lshr_b32 s100, s96, 5
	s_mul_i32 s100, s100, 7
	s_and_b32 vcc_lo, s96, 7
	s_add_u32 s100, s100, vcc_lo
	s_lshl_b32 s100, s100, 8
	s_add_u32 s100, s100, 0x7c00
	v_mov_b32_e32 v0, 4
.Lmy_pb_3:
	v_cmp_eq_u32_e32 vcc, 0, v1
	s_and_saveexec_b64 s[12:13], vcc
	s_cbranch_execz .LBB0_674
	s_bcnt1_i32_b64 s6, s[6:7]
	v_mov_b32_e32 v2, s6
	v_mov_b32_e32 v3, s100
	global_atomic_add v2, v3, v2, s[4:5] offset:1024 sc0
.LBB0_674:
	s_or_b64 exec, exec, s[12:13]
	buffer_inv sc1
	v_cvt_f32_u32_e32 v3, v0
	s_waitcnt vmcnt(0)
	v_readfirstlane_b32 s6, v2
	v_sub_u32_e32 v2, 0, v0
	v_rcp_iflag_f32_e32 v3, v3
	v_add_u32_e32 v4, s6, v1
	v_mul_f32_e32 v3, 0x4f7ffffe, v3
	v_cvt_u32_f32_e32 v3, v3
	v_mul_lo_u32 v1, v2, v3
	v_mul_hi_u32 v1, v3, v1
	v_add_u32_e32 v1, v3, v1
	v_mul_hi_u32 v1, v4, v1
	v_mul_lo_u32 v2, v1, v0
	v_sub_u32_e32 v2, v4, v2
	v_add_u32_e32 v3, 1, v1
	v_cmp_ge_u32_e32 vcc, v2, v0
	s_nop 1
	v_cndmask_b32_e32 v1, v1, v3, vcc
	v_sub_u32_e32 v3, v2, v0
	v_cndmask_b32_e32 v2, v2, v3, vcc
	v_add_u32_e32 v3, 1, v1
	v_cmp_ge_u32_e32 vcc, v2, v0
	v_add_u32_e32 v2, 1, v4
	s_nop 0
	v_cndmask_b32_e32 v1, v1, v3, vcc
	v_mul_lo_u32 v3, v0, v1
	v_add_u32_e32 v0, v3, v0
	v_cmp_ne_u32_e32 vcc, v2, v0
	s_and_saveexec_b64 s[6:7], vcc
	s_xor_b64 s[6:7], exec, s[6:7]
	s_cbranch_execz .LBB0_688
	v_readlane_b32 vcc_lo, v253, 2
	v_readlane_b32 vcc_hi, v253, 3
	s_nop 0
	s_and_b64 vcc, exec, vcc
	s_cbranch_vccnz .Lxb_gen_4
	v_mov_b32_e32 v4, v0
	v_mov_b32_e32 v5, s100
	s_mov_b32 s18, 0

; __device__ __forceinline__ unsigned xb_ld(unsigned* p)              { return __hip_atomic_load(p, __ATOMIC_RELAXED, __HIP_MEMORY_SCOPE_AGENT); }
; __device__ __forceinline__ void xcd_barrier_complete(unsigned* bar, unsigned x, unsigned& nloc, unsigned& nx, unsigned& uni) {
;     const unsigned G = gridDim.x * gridDim.y * gridDim.z;
;     unsigned sum, cnt, mine, sp = 0u;
;     for (;;) {
;         sum = 0u; cnt = 0u; mine = 0u;
; #pragma unroll
;         for (unsigned j = 0; j < 16; ++j) { const unsigned c = xb_ld(&bar[XB_XCNT(j)]); sum += c; cnt += (c > 0u) ? 1u : 0u; mine = (j == x) ? c : mine; }
; __device__ __forceinline__ void xcd_barrier(const XcdBarrier& b, const bool local_only = false) {
;     asm volatile("s_waitcnt vmcnt(0)" ::: "memory");
;     __syncthreads();
;     if (threadIdx.x == 0) {
;         unsigned* bar = b.bar;
;         __builtin_amdgcn_s_waitcnt(0);
;         unsigned nloc = b.st[0], nx = b.st[1];
;         if (nloc == 0u) { unsigned uni; xcd_barrier_complete(bar, b.x, nloc, nx, uni); b.st[0] = nloc; b.st[1] = nx; b.st[2] = uni; }
.LBB0_725:
	s_mov_b32 s101, 0
	v_readlane_b32 s0, v253, 6
	v_readlane_b32 s92, v255, 2
	s_add_i32 s48, s0, 2
	v_readlane_b32 s93, v255, 3
	s_cmp_ge_i32 s48, s93
	s_cbranch_scc1 .LBB0_736
	s_waitcnt vmcnt(0)
	s_waitcnt vmcnt(0) lgkmcnt(0)
	s_barrier
	s_mov_b64 s[0:1], exec
	v_readlane_b32 s4, v254, 18
	v_readlane_b32 s5, v254, 19
	v_readlane_b32 s94, v255, 10
	s_and_b64 s[4:5], s[0:1], s[4:5]
	v_readlane_b32 s95, v255, 11
	s_mov_b32 s96, s47
	v_readlane_b32 s97, v255, 4
	v_readlane_b32 s86, v255, 9
	s_mov_b64 exec, s[4:5]
	s_cbranch_execz .LBB0_780
	v_readlane_b32 s4, v254, 62
	s_load_dwordx2 s[8:9], s[94:95], 0x88
	s_waitcnt vmcnt(0) expcnt(0) lgkmcnt(0)
	v_mov_b32_e32 v0, s4
	ds_read_b32 v0, v0
	v_readlane_b32 s4, v254, 63
	s_waitcnt lgkmcnt(0)
	v_cmp_ne_u32_e32 vcc, 0, v0
	v_mov_b32_e32 v1, s4
	ds_read_b32 v6, v1
	s_cbranch_vccnz .LBB0_742
	s_add_u32 s56, s8, 0x1200
	s_addc_u32 s57, s9, 0
	s_add_u32 s46, s8, 0x1400
	s_addc_u32 s47, s9, 0
	s_add_u32 s52, s8, 0x1500
	s_addc_u32 s53, s9, 0
	s_add_u32 s50, s8, 0x1600
	s_addc_u32 s51, s9, 0
	s_add_u32 s44, s8, 0x1700
	s_addc_u32 s45, s9, 0
	s_add_u32 s42, s8, 0x1800
	s_addc_u32 s43, s9, 0
	s_add_u32 s40, s8, 0x1900
	s_addc_u32 s41, s9, 0
	s_add_u32 s38, s8, 0x1a00
	s_addc_u32 s39, s9, 0
	s_add_u32 s28, s8, 0x1b00
	s_addc_u32 s29, s9, 0
	s_add_u32 s26, s8, 0x1c00
	s_addc_u32 s27, s9, 0
	s_add_u32 s24, s8, 0x1d00
	v_readlane_b32 s6, v253, 0
	s_addc_u32 s25, s9, 0
	v_readlane_b32 s7, v253, 1
	s_add_u32 s22, s8, 0x1e00
	s_load_dwordx2 s[4:5], s[6:7], 0x4
	s_addc_u32 s23, s9, 0
	s_add_u32 s20, s8, 0x1f00
	s_addc_u32 s21, s9, 0
	s_add_u32 s18, s8, 0x2000
	s_addc_u32 s19, s9, 0
	s_waitcnt lgkmcnt(0)
	s_mul_i32 s62, s4, s3
	s_add_u32 s4, s8, 0x2100
	s_mul_i32 s62, s62, s5
	s_addc_u32 s5, s9, 0
	s_add_u32 s6, s8, 0x2200
	s_addc_u32 s7, s9, 0
	s_add_u32 s12, s8, 0x2300
	s_addc_u32 s13, s9, 0
	s_mov_b32 s63, 1
	s_branch .LBB0_730

; __device__ __forceinline__ unsigned xb_ld(unsigned* p)              { return __hip_atomic_load(p, __ATOMIC_RELAXED, __HIP_MEMORY_SCOPE_AGENT); }
; __device__ __forceinline__ void xcd_barrier_complete(unsigned* bar, unsigned x, unsigned& nloc, unsigned& nx, unsigned& uni) {
;     const unsigned G = gridDim.x * gridDim.y * gridDim.z;
;     unsigned sum, cnt, mine, sp = 0u;
;     for (;;) {
;         sum = 0u; cnt = 0u; mine = 0u;
; #pragma unroll
;         for (unsigned j = 0; j < 16; ++j) { const unsigned c = xb_ld(&bar[XB_XCNT(j)]); sum += c; cnt += (c > 0u) ? 1u : 0u; mine = (j == x) ? c : mine; }
; __device__ __forceinline__ void xcd_barrier(const XcdBarrier& b, const bool local_only = false) {
;     asm volatile("s_waitcnt vmcnt(0)" ::: "memory");
;     __syncthreads();
;     if (threadIdx.x == 0) {
;         unsigned* bar = b.bar;
;         __builtin_amdgcn_s_waitcnt(0);
;         unsigned nloc = b.st[0], nx = b.st[1];
;         if (nloc == 0u) { unsigned uni; xcd_barrier_complete(bar, b.x, nloc, nx, uni); b.st[0] = nloc; b.st[1] = nx; b.st[2] = uni; }
.LBB0_820:
	s_mov_b32 s101, 1
	v_readlane_b32 s4, v253, 6
	s_add_i32 s4, s4, 3
	s_cmp_ge_i32 s4, s93
	v_readlane_b32 s4, v255, 7
	v_readlane_b32 s5, v255, 8
	s_cbranch_scc1 .LBB0_832
	s_waitcnt vmcnt(0)
	s_waitcnt vmcnt(0) lgkmcnt(0)
	s_barrier
	s_mov_b64 s[8:9], exec
	v_readlane_b32 s4, v254, 18
	v_readlane_b32 s5, v254, 19
	s_and_b64 s[4:5], s[8:9], s[4:5]
	s_mov_b64 exec, s[4:5]
	s_cbranch_execz .LBB0_1127
	v_readlane_b32 s4, v254, 62
	s_waitcnt vmcnt(0) expcnt(0) lgkmcnt(0)
	s_nop 0
	v_mov_b32_e32 v0, s4
	ds_read_b32 v0, v0
	v_readlane_b32 s4, v254, 63
	s_waitcnt lgkmcnt(0)
	v_cmp_ne_u32_e32 vcc, 0, v0
	v_mov_b32_e32 v1, s4
	ds_read_b32 v6, v1
	s_cbranch_vccnz .LBB0_918
	s_add_u32 s56, s0, 0x1200
	s_addc_u32 s57, s1, 0
	s_add_u32 s46, s0, 0x1400
	s_addc_u32 s47, s1, 0
	s_add_u32 s52, s0, 0x1500
	s_addc_u32 s53, s1, 0
	s_add_u32 s50, s0, 0x1600
	s_addc_u32 s51, s1, 0
	s_add_u32 s44, s0, 0x1700
	s_addc_u32 s45, s1, 0
	s_add_u32 s42, s0, 0x1800
	s_addc_u32 s43, s1, 0
	s_add_u32 s40, s0, 0x1900
	s_addc_u32 s41, s1, 0
	s_add_u32 s38, s0, 0x1a00
	s_addc_u32 s39, s1, 0
	s_add_u32 s28, s0, 0x1b00
	s_addc_u32 s29, s1, 0
	s_add_u32 s26, s0, 0x1c00
	s_addc_u32 s27, s1, 0
	s_add_u32 s24, s0, 0x1d00
	v_readlane_b32 s6, v253, 0
	s_addc_u32 s25, s1, 0
	v_readlane_b32 s7, v253, 1
	s_add_u32 s22, s0, 0x1e00
	s_load_dwordx2 s[4:5], s[6:7], 0x4
	s_addc_u32 s23, s1, 0
	s_add_u32 s20, s0, 0x1f00
	s_addc_u32 s21, s1, 0
	s_add_u32 s18, s0, 0x2000
	s_addc_u32 s19, s1, 0
	s_waitcnt lgkmcnt(0)
	s_mul_i32 s48, s4, s3
	s_add_u32 s4, s0, 0x2100
	s_mul_i32 s48, s48, s5
	s_addc_u32 s5, s1, 0
	s_add_u32 s6, s0, 0x2200
	s_addc_u32 s7, s1, 0
	s_add_u32 s12, s0, 0x2300
	s_addc_u32 s13, s1, 0
	s_mov_b32 s62, 1
	s_branch .LBB0_825

; __device__ __forceinline__ unsigned xb_ld(unsigned* p)              { return __hip_atomic_load(p, __ATOMIC_RELAXED, __HIP_MEMORY_SCOPE_AGENT); }
; __device__ __forceinline__ void xcd_barrier_complete(unsigned* bar, unsigned x, unsigned& nloc, unsigned& nx, unsigned& uni) {
;     const unsigned G = gridDim.x * gridDim.y * gridDim.z;
;     unsigned sum, cnt, mine, sp = 0u;
;     for (;;) {
;         sum = 0u; cnt = 0u; mine = 0u;
; #pragma unroll
;         for (unsigned j = 0; j < 16; ++j) { const unsigned c = xb_ld(&bar[XB_XCNT(j)]); sum += c; cnt += (c > 0u) ? 1u : 0u; mine = (j == x) ? c : mine; }
; __device__ __forceinline__ void xcd_barrier(const XcdBarrier& b, const bool local_only = false) {
;     asm volatile("s_waitcnt vmcnt(0)" ::: "memory");
;     __syncthreads();
;     if (threadIdx.x == 0) {
;         unsigned* bar = b.bar;
;         __builtin_amdgcn_s_waitcnt(0);
;         unsigned nloc = b.st[0], nx = b.st[1];
;         if (nloc == 0u) { unsigned uni; xcd_barrier_complete(bar, b.x, nloc, nx, uni); b.st[0] = nloc; b.st[1] = nx; b.st[2] = uni; }
.LBB0_867:
	s_mov_b32 s101, 1
	v_readlane_b32 s4, v253, 6
	s_add_i32 s48, s4, 4
	s_cmp_ge_i32 s48, s93
	s_cbranch_scc1 .LBB0_957
	s_waitcnt vmcnt(0)
	s_waitcnt vmcnt(0) lgkmcnt(0)
	s_barrier
	s_mov_b64 s[8:9], exec
	v_readlane_b32 s4, v254, 18
	v_readlane_b32 s5, v254, 19
	s_and_b64 s[4:5], s[8:9], s[4:5]
	s_mov_b64 exec, s[4:5]
	s_cbranch_execz .LBB0_956
	v_readlane_b32 s4, v254, 62
	s_waitcnt vmcnt(0) expcnt(0) lgkmcnt(0)
	s_nop 0
	v_mov_b32_e32 v0, s4
	ds_read_b32 v0, v0
	v_readlane_b32 s4, v254, 63
	s_waitcnt lgkmcnt(0)
	v_cmp_ne_u32_e32 vcc, 0, v0
	v_mov_b32_e32 v1, s4
	ds_read_b32 v6, v1
	s_cbranch_vccnz .LBB0_883
	s_add_u32 s56, s0, 0x1200
	s_addc_u32 s57, s1, 0
	s_add_u32 s46, s0, 0x1400
	s_addc_u32 s47, s1, 0
	s_add_u32 s52, s0, 0x1500
	s_addc_u32 s53, s1, 0
	s_add_u32 s50, s0, 0x1600
	s_addc_u32 s51, s1, 0
	s_add_u32 s44, s0, 0x1700
	s_addc_u32 s45, s1, 0
	s_add_u32 s42, s0, 0x1800
	s_addc_u32 s43, s1, 0
	s_add_u32 s40, s0, 0x1900
	s_addc_u32 s41, s1, 0
	s_add_u32 s38, s0, 0x1a00
	s_addc_u32 s39, s1, 0
	s_add_u32 s28, s0, 0x1b00
	s_addc_u32 s29, s1, 0
	s_add_u32 s26, s0, 0x1c00
	s_addc_u32 s27, s1, 0
	s_add_u32 s24, s0, 0x1d00
	v_readlane_b32 s6, v253, 0
	s_addc_u32 s25, s1, 0
	v_readlane_b32 s7, v253, 1
	s_add_u32 s22, s0, 0x1e00
	s_load_dwordx2 s[4:5], s[6:7], 0x4
	s_addc_u32 s23, s1, 0
	s_add_u32 s20, s0, 0x1f00
	s_addc_u32 s21, s1, 0
	s_add_u32 s18, s0, 0x2000
	s_addc_u32 s19, s1, 0
	s_waitcnt lgkmcnt(0)
	s_mul_i32 s62, s4, s3
	s_add_u32 s4, s0, 0x2100
	s_mul_i32 s62, s62, s5
	s_addc_u32 s5, s1, 0
	s_add_u32 s6, s0, 0x2200
	s_addc_u32 s7, s1, 0
	s_add_u32 s12, s0, 0x2300
	s_addc_u32 s13, s1, 0
	s_mov_b32 s63, 1
	s_branch .LBB0_872

; __device__ __forceinline__ unsigned xb_add(unsigned* p, unsigned v) { return __hip_atomic_fetch_add(p, v, __ATOMIC_RELAXED, __HIP_MEMORY_SCOPE_AGENT); }
; __device__ __forceinline__ void xcd_barrier(const XcdBarrier& b, const bool local_only = false) {
;     ...
;         const unsigned old = xb_add(&bar[XB_XSUB(b.x)], 1u);
;         const unsigned gen = old / nloc;
;         if (old + 1u == (gen + 1u) * nloc) {
.LBB0_883:
	v_readlane_b32 s4, v254, 13
	s_lshl_b32 s4, s4, 2
	s_mov_b64 s[6:7], exec
	s_add_u32 s4, s0, s4
	s_addc_u32 s5, s1, 0
	v_mbcnt_lo_u32_b32 v1, s6, 0
	s_add_u32 s4, s4, 0x1000
	v_mbcnt_hi_u32_b32 v1, s7, v1
	s_addc_u32 s5, s5, 0
	s_mov_b32 s100, 0x1000
	s_cmp_eq_u32 s101, 0
	s_cbranch_scc1 .Lmy_pb_5
	v_readlane_b32 vcc_lo, v253, 2
	v_readlane_b32 vcc_hi, v253, 3
	s_nop 0
	s_and_b64 vcc, exec, vcc
	s_cbranch_vccnz .Lmy_pb_5
	s_lshr_b32 s100, s96, 5
	s_mul_i32 s100, s100, 7
	s_and_b32 vcc_lo, s96, 7
	s_add_u32 s100, s100, vcc_lo
	s_lshl_b32 s100, s100, 8
	s_add_u32 s100, s100, 0x7c00
	v_mov_b32_e32 v0, 4

; __device__ __forceinline__ unsigned xb_ld(unsigned* p)              { return __hip_atomic_load(p, __ATOMIC_RELAXED, __HIP_MEMORY_SCOPE_AGENT); }
; __device__ __forceinline__ void xcd_barrier_complete(unsigned* bar, unsigned x, unsigned& nloc, unsigned& nx, unsigned& uni) {
;     const unsigned G = gridDim.x * gridDim.y * gridDim.z;
;     unsigned sum, cnt, mine, sp = 0u;
;     for (;;) {
;         sum = 0u; cnt = 0u; mine = 0u;
; #pragma unroll
;         for (unsigned j = 0; j < 16; ++j) { const unsigned c = xb_ld(&bar[XB_XCNT(j)]); sum += c; cnt += (c > 0u) ? 1u : 0u; mine = (j == x) ? c : mine; }
; __device__ __forceinline__ void xcd_barrier(const XcdBarrier& b, const bool local_only = false) {
;     asm volatile("s_waitcnt vmcnt(0)" ::: "memory");
;     __syncthreads();
;     if (threadIdx.x == 0) {
;         unsigned* bar = b.bar;
;         __builtin_amdgcn_s_waitcnt(0);
;         unsigned nloc = b.st[0], nx = b.st[1];
;         if (nloc == 0u) { unsigned uni; xcd_barrier_complete(bar, b.x, nloc, nx, uni); b.st[0] = nloc; b.st[1] = nx; b.st[2] = uni; }
.LBB0_1065:
	s_mov_b32 s101, 0
	v_readlane_b32 s4, v253, 6
	s_add_i32 s4, s4, 5
	s_cmp_ge_i32 s4, s93
	v_writelane_b32 v253, s4, 6
	s_cbranch_scc1 .LBB0_1076
	s_waitcnt vmcnt(0)
	s_waitcnt vmcnt(0) lgkmcnt(0)
	s_barrier
	s_mov_b64 s[8:9], exec
	v_readlane_b32 s4, v254, 18
	v_readlane_b32 s5, v254, 19
	s_and_b64 s[4:5], s[8:9], s[4:5]
	s_mov_b64 exec, s[4:5]
	s_cbranch_execz .LBB0_188
	v_readlane_b32 s4, v254, 62
	s_waitcnt vmcnt(0) expcnt(0) lgkmcnt(0)
	s_nop 0
	v_mov_b32_e32 v0, s4
	ds_read_b32 v0, v0
	v_readlane_b32 s4, v254, 63
	s_waitcnt lgkmcnt(0)
	v_cmp_ne_u32_e32 vcc, 0, v0
	v_mov_b32_e32 v1, s4
	ds_read_b32 v6, v1
	s_cbranch_vccnz .LBB0_1082
	s_add_u32 s56, s0, 0x1200
	s_addc_u32 s57, s1, 0
	s_add_u32 s46, s0, 0x1400
	s_addc_u32 s47, s1, 0
	s_add_u32 s52, s0, 0x1500
	s_addc_u32 s53, s1, 0
	s_add_u32 s50, s0, 0x1600
	s_addc_u32 s51, s1, 0
	s_add_u32 s44, s0, 0x1700
	s_addc_u32 s45, s1, 0
	s_add_u32 s42, s0, 0x1800
	s_addc_u32 s43, s1, 0
	s_add_u32 s40, s0, 0x1900
	s_addc_u32 s41, s1, 0
	s_add_u32 s38, s0, 0x1a00
	s_addc_u32 s39, s1, 0
	s_add_u32 s28, s0, 0x1b00
	s_addc_u32 s29, s1, 0
	s_add_u32 s26, s0, 0x1c00
	s_addc_u32 s27, s1, 0
	s_add_u32 s24, s0, 0x1d00
	v_readlane_b32 s6, v253, 0
	s_addc_u32 s25, s1, 0
	v_readlane_b32 s7, v253, 1
	s_add_u32 s22, s0, 0x1e00
	s_load_dwordx2 s[4:5], s[6:7], 0x4
	s_addc_u32 s23, s1, 0
	s_add_u32 s20, s0, 0x1f00
	s_addc_u32 s21, s1, 0
	s_add_u32 s18, s0, 0x2000
	s_addc_u32 s19, s1, 0
	s_waitcnt lgkmcnt(0)
	s_mul_i32 s48, s4, s3
	s_add_u32 s4, s0, 0x2100
	s_mul_i32 s48, s48, s5
	s_addc_u32 s5, s1, 0
	s_add_u32 s6, s0, 0x2200
	s_addc_u32 s7, s1, 0
	s_add_u32 s12, s0, 0x2300
	s_addc_u32 s13, s1, 0
	s_mov_b32 s62, 1
	s_branch .LBB0_1070
